# c21 with the logit GEMV A-operand staging double-buffered in 256-byte row chunks
# speedup vs baseline: 1.0080x; 1.0049x over previous
.LBB0_989:
	s_nop 0
	s_nop 0
	s_cmp_gt_i32 s92, 4
	s_cselect_b64 s[8:9], -1, 0
	s_cmp_lt_i32 s92, 5
	s_cselect_b64 s[0:1], -1, 0
	s_cmp_gt_i32 s93, 4
	s_cselect_b64 s[2:3], -1, 0
	s_and_b64 s[0:1], s[0:1], s[2:3]
	s_andn2_b64 vcc, exec, s[0:1]
	s_cbranch_vccnz .LBB0_1185
	v_readlane_b32 s0, v254, 16
	v_readlane_b32 s6, v254, 22
	v_readlane_b32 s7, v254, 23
	s_add_u32 s33, s6, 0x6000000
	s_addc_u32 s34, s7, 0
	s_add_u32 s14, s6, 0x500000
	s_addc_u32 s15, s7, 0
	v_mbcnt_lo_u32_b32 v24, -1, 0
	v_mbcnt_hi_u32_b32 v24, -1, v24
	s_cmpk_lt_i32 s69, 0x100
	v_and_b32_e32 v25, 15, v24
	v_readlane_b32 s1, v254, 17
	v_readlane_b32 s2, v254, 18
	v_readlane_b32 s3, v254, 19
	v_readlane_b32 s4, v254, 20
	v_readlane_b32 s5, v254, 21
	s_cbranch_scc1 .LBB0_992
	v_and_b32_e32 v8, 15, v24
	s_cbranch_execz .LBB0_993
	s_branch .LBB0_1002

.LBB0_997:
	s_add_i32 s6, s6, s10
	v_add_u32_e32 v0, s6, v25
	v_ashrrev_i32_e32 v1, 31, v0
	v_lshlrev_b64 v[0:1], 12, v[0:1]
	v_lshl_add_u64 v[22:23], v[8:9], 0, v[0:1]
	v_readlane_b32 s35, v254, 24
	v_mbcnt_lo_u32_b32 v90, -1, 0
	v_mbcnt_hi_u32_b32 v90, -1, v90
	v_readfirstlane_b32 s36, v22
	v_readfirstlane_b32 s37, v23
	v_readfirstlane_b32 s38, v12
	v_readfirstlane_b32 s39, v13
	s_lshr_b32 s40, s35, 6
	s_lshr_b32 s41, s35, 8
	s_and_b32 s42, s40, 3
	s_lshl_b32 s43, s41, 11
	s_sub_u32 s44, s38, s43
	s_subb_u32 s45, s39, 0
	s_lshl_b32 s49, s40, 13
	s_add_i32 s49, s49, 0x10000
	v_and_b32_e32 v91, 31, v90
	v_lshrrev_b32_e32 v92, 5, v90
	v_and_b32_e32 v93, 15, v90
	v_lshrrev_b32_e32 v94, 4, v90
	s_add_i32 s46, s41, 0
	v_xor_b32_e32 v95, s46, v91
	v_lshlrev_b32_e32 v95, 4, v95
	v_lshl_add_u32 v95, v92, 9, v95
	s_lshl_b32 s47, s46, 12
	s_lshl_b32 s48, s42, 10
	s_add_i32 s47, s47, s48
	v_add_u32_e32 v95, s47, v95
	s_lshl_b32 s48, s40, 10
	s_add_i32 m0, s48, 0x0
	s_nop 0
	global_load_lds_dwordx4 v95, s[44:45]
	s_add_i32 s46, s41, 2
	v_xor_b32_e32 v95, s46, v91
	v_lshlrev_b32_e32 v95, 4, v95
	v_lshl_add_u32 v95, v92, 9, v95
	s_lshl_b32 s47, s46, 12
	s_lshl_b32 s48, s42, 10
	s_add_i32 s47, s47, s48
	v_add_u32_e32 v95, s47, v95
	s_lshl_b32 s48, s40, 10
	s_add_i32 m0, s48, 0x2000
	s_nop 0
	global_load_lds_dwordx4 v95, s[44:45]
	s_add_i32 s46, s41, 4
	v_xor_b32_e32 v95, s46, v91
	v_lshlrev_b32_e32 v95, 4, v95
	v_lshl_add_u32 v95, v92, 9, v95
	s_lshl_b32 s47, s46, 12
	s_lshl_b32 s48, s42, 10
	s_add_i32 s47, s47, s48
	v_add_u32_e32 v95, s47, v95
	s_lshl_b32 s48, s40, 10
	s_add_i32 m0, s48, 0x4000
	s_nop 0
	global_load_lds_dwordx4 v95, s[44:45]
	s_add_i32 s46, s41, 6
	v_xor_b32_e32 v95, s46, v91
	v_lshlrev_b32_e32 v95, 4, v95
	v_lshl_add_u32 v95, v92, 9, v95
	s_lshl_b32 s47, s46, 12
	s_lshl_b32 s48, s42, 10
	s_add_i32 s47, s47, s48
	v_add_u32_e32 v95, s47, v95
	s_lshl_b32 s48, s40, 10
	s_add_i32 m0, s48, 0x6000
	s_nop 0
	global_load_lds_dwordx4 v95, s[44:45]
	s_add_i32 s46, s41, 8
	v_xor_b32_e32 v95, s46, v91
	v_lshlrev_b32_e32 v95, 4, v95
	v_lshl_add_u32 v95, v92, 9, v95
	s_lshl_b32 s47, s46, 12
	s_lshl_b32 s48, s42, 10
	s_add_i32 s47, s47, s48
	v_add_u32_e32 v95, s47, v95
	s_lshl_b32 s48, s40, 10
	s_add_i32 m0, s48, 0x8000
	s_nop 0
	global_load_lds_dwordx4 v95, s[44:45]
	s_add_i32 s46, s41, 10
	v_xor_b32_e32 v95, s46, v91
	v_lshlrev_b32_e32 v95, 4, v95
	v_lshl_add_u32 v95, v92, 9, v95
	s_lshl_b32 s47, s46, 12
	s_lshl_b32 s48, s42, 10
	s_add_i32 s47, s47, s48
	v_add_u32_e32 v95, s47, v95
	s_lshl_b32 s48, s40, 10
	s_add_i32 m0, s48, 0xa000
	s_nop 0
	global_load_lds_dwordx4 v95, s[44:45]
	s_add_i32 s46, s41, 12
	v_xor_b32_e32 v95, s46, v91
	v_lshlrev_b32_e32 v95, 4, v95
	v_lshl_add_u32 v95, v92, 9, v95
	s_lshl_b32 s47, s46, 12
	s_lshl_b32 s48, s42, 10
	s_add_i32 s47, s47, s48
	v_add_u32_e32 v95, s47, v95
	s_lshl_b32 s48, s40, 10
	s_add_i32 m0, s48, 0xc000
	s_nop 0
	global_load_lds_dwordx4 v95, s[44:45]
	s_add_i32 s46, s41, 14
	v_xor_b32_e32 v95, s46, v91
	v_lshlrev_b32_e32 v95, 4, v95
	v_lshl_add_u32 v95, v92, 9, v95
	s_lshl_b32 s47, s46, 12
	s_lshl_b32 s48, s42, 10
	s_add_i32 s47, s47, s48
	v_add_u32_e32 v95, s47, v95
	s_lshl_b32 s48, s40, 10
	s_add_i32 m0, s48, 0xe000
	s_nop 0
	global_load_lds_dwordx4 v95, s[44:45]
	v_add_u32_e32 v96, 0, v94
	v_xor_b32_e32 v96, v96, v93
	v_lshlrev_b32_e32 v96, 4, v96
	v_lshl_add_u32 v108, v93, 12, v96
	v_add_u32_e32 v108, s43, v108
	v_add_u32_e32 v96, 4, v94
	v_xor_b32_e32 v96, v96, v93
	v_lshlrev_b32_e32 v96, 4, v96
	v_lshl_add_u32 v109, v93, 12, v96
	v_add_u32_e32 v109, s43, v109
	v_add_u32_e32 v96, 8, v94
	v_xor_b32_e32 v96, v96, v93
	v_lshlrev_b32_e32 v96, 4, v96
	v_lshl_add_u32 v110, v93, 12, v96
	v_add_u32_e32 v110, s43, v110
	v_add_u32_e32 v96, 12, v94
	v_xor_b32_e32 v96, v96, v93
	v_lshlrev_b32_e32 v96, 4, v96
	v_lshl_add_u32 v111, v93, 12, v96
	v_add_u32_e32 v111, s43, v111
	v_add_u32_e32 v96, 16, v94
	v_xor_b32_e32 v96, v96, v93
	v_lshlrev_b32_e32 v96, 4, v96
	v_lshl_add_u32 v112, v93, 12, v96
	v_add_u32_e32 v112, s43, v112
	v_add_u32_e32 v96, 20, v94
	v_xor_b32_e32 v96, v96, v93
	v_lshlrev_b32_e32 v96, 4, v96
	v_lshl_add_u32 v113, v93, 12, v96
	v_add_u32_e32 v113, s43, v113
	v_add_u32_e32 v96, 24, v94
	v_xor_b32_e32 v96, v96, v93
	v_lshlrev_b32_e32 v96, 4, v96
	v_lshl_add_u32 v114, v93, 12, v96
	v_add_u32_e32 v114, s43, v114
	v_add_u32_e32 v96, 28, v94
	v_xor_b32_e32 v96, v96, v93
	v_lshlrev_b32_e32 v96, 4, v96
	v_lshl_add_u32 v115, v93, 12, v96
	v_add_u32_e32 v115, s43, v115
	v_and_b32_e32 v97, 15, v90
	v_add_u32_e32 v96, 0, v94
	v_xor_b32_e32 v96, v96, v93
	v_lshlrev_b32_e32 v96, 4, v96
	v_lshl_add_u32 v100, v93, 8, v96
	v_add_u32_e32 v100, s49, v100
	v_add_u32_e32 v96, 4, v94
	v_xor_b32_e32 v96, v96, v93
	v_lshlrev_b32_e32 v96, 4, v96
	v_lshl_add_u32 v101, v93, 8, v96
	v_add_u32_e32 v101, s49, v101
	v_add_u32_e32 v96, 8, v94
	v_xor_b32_e32 v96, v96, v93
	v_lshlrev_b32_e32 v96, 4, v96
	v_lshl_add_u32 v102, v93, 8, v96
	v_add_u32_e32 v102, s49, v102
	v_add_u32_e32 v96, 12, v94
	v_xor_b32_e32 v96, v96, v93
	v_lshlrev_b32_e32 v96, 4, v96
	v_lshl_add_u32 v103, v93, 8, v96
	v_add_u32_e32 v103, s49, v103
	v_add_u32_e32 v96, 0, v94
	v_xor_b32_e32 v98, v96, v97
	v_lshlrev_b32_e32 v98, 4, v98
	v_lshl_add_u32 v116, v96, 12, v98
	v_add_u32_e32 v96, 4, v94
	v_xor_b32_e32 v98, v96, v97
	v_lshlrev_b32_e32 v98, 4, v98
	v_lshl_add_u32 v117, v96, 12, v98
	v_add_u32_e32 v96, 8, v94
	v_xor_b32_e32 v98, v96, v97
	v_lshlrev_b32_e32 v98, 4, v98
	v_lshl_add_u32 v118, v96, 12, v98
	v_add_u32_e32 v96, 12, v94
	v_xor_b32_e32 v98, v96, v97
	v_lshlrev_b32_e32 v98, 4, v98
	v_lshl_add_u32 v119, v96, 12, v98
	s_mov_b64 s[50:51], s[36:37]
	s_add_i32 m0, s49, 0x0
	s_nop 0
	global_load_lds_dwordx4 v116, s[50:51]
	s_add_i32 m0, s49, 0x400
	s_nop 0
	global_load_lds_dwordx4 v117, s[50:51]
	s_add_i32 m0, s49, 0x800
	s_nop 0
	global_load_lds_dwordx4 v118, s[50:51]
	s_add_i32 m0, s49, 0xc00
	s_nop 0
	global_load_lds_dwordx4 v119, s[50:51]
	s_add_u32 s50, s36, 0x100
	s_addc_u32 s51, s37, 0
	s_add_i32 m0, s49, 0x1000
	s_nop 0
	global_load_lds_dwordx4 v116, s[50:51]
	s_add_i32 m0, s49, 0x1400
	s_nop 0
	global_load_lds_dwordx4 v117, s[50:51]
	s_add_i32 m0, s49, 0x1800
	s_nop 0
	global_load_lds_dwordx4 v118, s[50:51]
	s_add_i32 m0, s49, 0x1c00
	s_nop 0
	global_load_lds_dwordx4 v119, s[50:51]
	s_waitcnt vmcnt(4)
	s_barrier
	ds_read_b128 v[124:127], v100
	ds_read_b128 v[140:143], v108
	ds_read_b128 v[128:131], v101
	ds_read_b128 v[144:147], v109
	ds_read_b128 v[132:135], v102
	ds_read_b128 v[148:151], v110
	ds_read_b128 v[136:139], v103
	ds_read_b128 v[152:155], v111
	s_waitcnt lgkmcnt(0)
	s_add_u32 s50, s36, 0x200
	s_addc_u32 s51, s37, 0
	s_add_i32 m0, s49, 0x0
	s_nop 0
	global_load_lds_dwordx4 v116, s[50:51]
	s_add_i32 m0, s49, 0x400
	s_nop 0
	global_load_lds_dwordx4 v117, s[50:51]
	s_add_i32 m0, s49, 0x800
	s_nop 0
	global_load_lds_dwordx4 v118, s[50:51]
	s_add_i32 m0, s49, 0xc00
	s_nop 0
	global_load_lds_dwordx4 v119, s[50:51]
	v_mfma_f32_16x16x32_bf16 v[0:3], v[124:127], v[140:143], 0
	v_mfma_f32_16x16x32_bf16 v[0:3], v[128:131], v[144:147], v[0:3]
	v_mfma_f32_16x16x32_bf16 v[0:3], v[132:135], v[148:151], v[0:3]
	v_mfma_f32_16x16x32_bf16 v[0:3], v[136:139], v[152:155], v[0:3]
	s_waitcnt vmcnt(4)
	ds_read_b128 v[124:127], v100 offset:4096
	ds_read_b128 v[140:143], v112
	ds_read_b128 v[128:131], v101 offset:4096
	ds_read_b128 v[144:147], v113
	ds_read_b128 v[132:135], v102 offset:4096
	ds_read_b128 v[148:151], v114
	ds_read_b128 v[136:139], v103 offset:4096
	ds_read_b128 v[152:155], v115
	s_waitcnt lgkmcnt(0)
	s_add_u32 s50, s36, 0x300
	s_addc_u32 s51, s37, 0
	s_add_i32 m0, s49, 0x1000
	s_nop 0
	global_load_lds_dwordx4 v116, s[50:51]
	s_add_i32 m0, s49, 0x1400
	s_nop 0
	global_load_lds_dwordx4 v117, s[50:51]
	s_add_i32 m0, s49, 0x1800
	s_nop 0
	global_load_lds_dwordx4 v118, s[50:51]
	s_add_i32 m0, s49, 0x1c00
	s_nop 0
	global_load_lds_dwordx4 v119, s[50:51]
	v_mfma_f32_16x16x32_bf16 v[0:3], v[124:127], v[140:143], v[0:3]
	v_mfma_f32_16x16x32_bf16 v[0:3], v[128:131], v[144:147], v[0:3]
	v_mfma_f32_16x16x32_bf16 v[0:3], v[132:135], v[148:151], v[0:3]
	v_mfma_f32_16x16x32_bf16 v[0:3], v[136:139], v[152:155], v[0:3]
	s_waitcnt vmcnt(4)
	ds_read_b128 v[124:127], v100
	ds_read_b128 v[140:143], v108 offset:512
	ds_read_b128 v[128:131], v101
	ds_read_b128 v[144:147], v109 offset:512
	ds_read_b128 v[132:135], v102
	ds_read_b128 v[148:151], v110 offset:512
	ds_read_b128 v[136:139], v103
	ds_read_b128 v[152:155], v111 offset:512
	s_waitcnt lgkmcnt(0)
	s_add_u32 s50, s36, 0x400
	s_addc_u32 s51, s37, 0
	s_add_i32 m0, s49, 0x0
	s_nop 0
	global_load_lds_dwordx4 v116, s[50:51]
	s_add_i32 m0, s49, 0x400
	s_nop 0
	global_load_lds_dwordx4 v117, s[50:51]
	s_add_i32 m0, s49, 0x800
	s_nop 0
	global_load_lds_dwordx4 v118, s[50:51]
	s_add_i32 m0, s49, 0xc00
	s_nop 0
	global_load_lds_dwordx4 v119, s[50:51]
	v_mfma_f32_16x16x32_bf16 v[0:3], v[124:127], v[140:143], v[0:3]
	v_mfma_f32_16x16x32_bf16 v[0:3], v[128:131], v[144:147], v[0:3]
	v_mfma_f32_16x16x32_bf16 v[0:3], v[132:135], v[148:151], v[0:3]
	v_mfma_f32_16x16x32_bf16 v[0:3], v[136:139], v[152:155], v[0:3]
	s_waitcnt vmcnt(4)
	ds_read_b128 v[124:127], v100 offset:4096
	ds_read_b128 v[140:143], v112 offset:512
	ds_read_b128 v[128:131], v101 offset:4096
	ds_read_b128 v[144:147], v113 offset:512
	ds_read_b128 v[132:135], v102 offset:4096
	ds_read_b128 v[148:151], v114 offset:512
	ds_read_b128 v[136:139], v103 offset:4096
	ds_read_b128 v[152:155], v115 offset:512
	s_waitcnt lgkmcnt(0)
	s_add_u32 s50, s36, 0x500
	s_addc_u32 s51, s37, 0
	s_add_i32 m0, s49, 0x1000
	s_nop 0
	global_load_lds_dwordx4 v116, s[50:51]
	s_add_i32 m0, s49, 0x1400
	s_nop 0
	global_load_lds_dwordx4 v117, s[50:51]
	s_add_i32 m0, s49, 0x1800
	s_nop 0
	global_load_lds_dwordx4 v118, s[50:51]
	s_add_i32 m0, s49, 0x1c00
	s_nop 0
	global_load_lds_dwordx4 v119, s[50:51]
	v_mfma_f32_16x16x32_bf16 v[0:3], v[124:127], v[140:143], v[0:3]
	v_mfma_f32_16x16x32_bf16 v[0:3], v[128:131], v[144:147], v[0:3]
	v_mfma_f32_16x16x32_bf16 v[0:3], v[132:135], v[148:151], v[0:3]
	v_mfma_f32_16x16x32_bf16 v[0:3], v[136:139], v[152:155], v[0:3]
	s_waitcnt vmcnt(4)
	ds_read_b128 v[124:127], v100
	ds_read_b128 v[140:143], v108 offset:1024
	ds_read_b128 v[128:131], v101
	ds_read_b128 v[144:147], v109 offset:1024
	ds_read_b128 v[132:135], v102
	ds_read_b128 v[148:151], v110 offset:1024
	ds_read_b128 v[136:139], v103
	ds_read_b128 v[152:155], v111 offset:1024
	s_waitcnt lgkmcnt(0)
	s_add_u32 s50, s36, 0x600
	s_addc_u32 s51, s37, 0
	s_add_i32 m0, s49, 0x0
	s_nop 0
	global_load_lds_dwordx4 v116, s[50:51]
	s_add_i32 m0, s49, 0x400
	s_nop 0
	global_load_lds_dwordx4 v117, s[50:51]
	s_add_i32 m0, s49, 0x800
	s_nop 0
	global_load_lds_dwordx4 v118, s[50:51]
	s_add_i32 m0, s49, 0xc00
	s_nop 0
	global_load_lds_dwordx4 v119, s[50:51]
	v_mfma_f32_16x16x32_bf16 v[0:3], v[124:127], v[140:143], v[0:3]
	v_mfma_f32_16x16x32_bf16 v[0:3], v[128:131], v[144:147], v[0:3]
	v_mfma_f32_16x16x32_bf16 v[0:3], v[132:135], v[148:151], v[0:3]
	v_mfma_f32_16x16x32_bf16 v[0:3], v[136:139], v[152:155], v[0:3]
	s_waitcnt vmcnt(4)
	ds_read_b128 v[124:127], v100 offset:4096
	ds_read_b128 v[140:143], v112 offset:1024
	ds_read_b128 v[128:131], v101 offset:4096
	ds_read_b128 v[144:147], v113 offset:1024
	ds_read_b128 v[132:135], v102 offset:4096
	ds_read_b128 v[148:151], v114 offset:1024
	ds_read_b128 v[136:139], v103 offset:4096
	ds_read_b128 v[152:155], v115 offset:1024
	s_waitcnt lgkmcnt(0)
	s_add_u32 s50, s36, 0x700
	s_addc_u32 s51, s37, 0
	s_add_i32 m0, s49, 0x1000
	s_nop 0
	global_load_lds_dwordx4 v116, s[50:51]
	s_add_i32 m0, s49, 0x1400
	s_nop 0
	global_load_lds_dwordx4 v117, s[50:51]
	s_add_i32 m0, s49, 0x1800
	s_nop 0
	global_load_lds_dwordx4 v118, s[50:51]
	s_add_i32 m0, s49, 0x1c00
	s_nop 0
	global_load_lds_dwordx4 v119, s[50:51]
	v_mfma_f32_16x16x32_bf16 v[0:3], v[124:127], v[140:143], v[0:3]
	v_mfma_f32_16x16x32_bf16 v[0:3], v[128:131], v[144:147], v[0:3]
	v_mfma_f32_16x16x32_bf16 v[0:3], v[132:135], v[148:151], v[0:3]
	v_mfma_f32_16x16x32_bf16 v[0:3], v[136:139], v[152:155], v[0:3]
	s_waitcnt vmcnt(4)
	ds_read_b128 v[124:127], v100
	ds_read_b128 v[140:143], v108 offset:1536
	ds_read_b128 v[128:131], v101
	ds_read_b128 v[144:147], v109 offset:1536
	ds_read_b128 v[132:135], v102
	ds_read_b128 v[148:151], v110 offset:1536
	ds_read_b128 v[136:139], v103
	ds_read_b128 v[152:155], v111 offset:1536
	s_waitcnt lgkmcnt(0)
	v_mfma_f32_16x16x32_bf16 v[0:3], v[124:127], v[140:143], v[0:3]
	v_mfma_f32_16x16x32_bf16 v[0:3], v[128:131], v[144:147], v[0:3]
	v_mfma_f32_16x16x32_bf16 v[0:3], v[132:135], v[148:151], v[0:3]
	v_mfma_f32_16x16x32_bf16 v[0:3], v[136:139], v[152:155], v[0:3]
	s_waitcnt vmcnt(0)
	ds_read_b128 v[124:127], v100 offset:4096
	ds_read_b128 v[140:143], v112 offset:1536
	ds_read_b128 v[128:131], v101 offset:4096
	ds_read_b128 v[144:147], v113 offset:1536
	ds_read_b128 v[132:135], v102 offset:4096
	ds_read_b128 v[148:151], v114 offset:1536
	ds_read_b128 v[136:139], v103 offset:4096
	ds_read_b128 v[152:155], v115 offset:1536
	s_waitcnt lgkmcnt(0)
	v_mfma_f32_16x16x32_bf16 v[0:3], v[124:127], v[140:143], v[0:3]
	v_mfma_f32_16x16x32_bf16 v[0:3], v[128:131], v[144:147], v[0:3]
	v_mfma_f32_16x16x32_bf16 v[0:3], v[132:135], v[148:151], v[0:3]
	v_mfma_f32_16x16x32_bf16 v[0:3], v[136:139], v[152:155], v[0:3]
	s_and_b64 vcc, exec, s[2:3]
	s_cbranch_vccnz .LBB0_999
	s_nop 6
	ds_write_b128 v27, v[0:3]
